# prep phase: beta load issued with g load; K fragments of tile rows 2,3 requested together ahead of their MFMAs (counted vmcnt instead of 8 serialized round trips)
# baseline (speedup 1.0000x reference)
; __device__ __forceinline__ void phase_prep(const Args& a, PG8_LAS unsigned char* lds) {
;     ...
;         float gv = gB[(r0 + lane) * 4 + h];
; #pragma unroll
;         for (int off = 1; off < 64; off <<= 1) { const float t = __shfl_up(gv, off); if (lane >= off) gv += t; }
;         const float g63 = __shfl(gv, 63);
;         if (lw == 0) { sG[lane] = gv; sB[lane] = betaB[(r0 + lane) * 4 + h]; sE[lane] = __expf(gv); sK[lane] = __expf(g63 - gv); }
;         if ((tid & 255) == 0) glast[item] = __expf(g63);
.LBB0_255:
	s_lshl_b64 vcc, s[18:19], 8
	v_mov_b32_e32 v129, vcc_hi
	v_or_b32_e32 v128, vcc_lo, v98
	s_mov_b32 s27, s15
	v_lshl_add_u64 v[128:129], v[128:129], 0, s[26:27]
	v_lshl_add_u64 v[230:231], v[128:129], 2, s[8:9]
	global_load_dword v107, v[230:231], off
	v_readlane_b32 s100, v253, 49
	v_readlane_b32 s101, v253, 50
	s_nop 1
	v_lshl_add_u64 v[232:233], v[128:129], 2, s[100:101]
	global_load_dword v111, v[232:233], off
	v_readlane_b32 s40, v253, 59
	v_readlane_b32 s41, v253, 60
	s_waitcnt vmcnt(0)
	ds_bpermute_b32 v109, v131, v107
	s_waitcnt lgkmcnt(0)
	v_add_f32_e32 v109, v107, v109
	v_cndmask_b32_e64 v107, v109, v107, s[62:63]
	ds_bpermute_b32 v109, v132, v107
	s_waitcnt lgkmcnt(0)
	v_add_f32_e32 v109, v107, v109
	v_cndmask_b32_e64 v107, v109, v107, s[40:41]
	ds_bpermute_b32 v109, v133, v107
	v_readlane_b32 s40, v253, 61
	v_readlane_b32 s41, v253, 62
	s_waitcnt lgkmcnt(0)
	v_add_f32_e32 v109, v107, v109
	v_cndmask_b32_e64 v107, v109, v107, s[40:41]
	ds_bpermute_b32 v109, v134, v107
	v_readlane_b32 s40, v253, 63
	v_readlane_b32 s41, v252, 0
	s_waitcnt lgkmcnt(0)
	v_add_f32_e32 v109, v107, v109
	v_cndmask_b32_e64 v107, v109, v107, s[40:41]
	ds_bpermute_b32 v109, v135, v107
	v_readlane_b32 s40, v252, 1
	v_readlane_b32 s41, v252, 2
	s_waitcnt lgkmcnt(0)
	v_add_f32_e32 v109, v107, v109
	v_cndmask_b32_e64 v107, v109, v107, s[40:41]
	ds_bpermute_b32 v109, v136, v107
	v_readlane_b32 s40, v252, 3
	v_readlane_b32 s41, v252, 4
	s_waitcnt lgkmcnt(0)
	v_add_f32_e32 v109, v107, v109
	v_cndmask_b32_e64 v109, v109, v107, s[40:41]
	ds_bpermute_b32 v107, v99, v109
	v_readlane_b32 s40, v253, 55
	v_readlane_b32 s41, v253, 56
	s_andn2_b64 vcc, exec, s[40:41]
	s_cbranch_vccnz .LBB0_257
	v_readlane_b32 s40, v253, 49
	v_readlane_b32 s41, v253, 50
	s_waitcnt lgkmcnt(0)
	v_sub_f32_e32 v115, v107, v109
	v_mul_f32_e32 v113, 0x3fb8aa3b, v109
	v_lshl_add_u64 v[128:129], v[128:129], 2, s[40:41]
	v_mul_f32_e32 v115, 0x3fb8aa3b, v115
	v_exp_f32_e32 v113, v113
	v_exp_f32_e32 v115, v115
	s_waitcnt vmcnt(0)
	ds_write2st64_b32 v130, v109, v111 offset1:1
	ds_write2st64_b32 v130, v113, v115 offset0:2 offset1:3

; #define MFMA16(a, b, c) __builtin_amdgcn_mfma_f32_16x16x32_bf16((a), (b), (c), 0, 0, 0)
; __device__ __forceinline__ void phase_prep(const Args& a, PG8_LAS unsigned char* lds) {
;     ...
; #pragma unroll
;             for (int tj = 0; tj < 4; ++tj) {
;                 f32x4 ckk = {0.f, 0.f, 0.f, 0.f}, cqk = {0.f, 0.f, 0.f, 0.f};
; #pragma unroll
;                 for (int s = 0; s < 4; ++s) { const bf16x8 bk = (tj < 2) ? bkf[tj & 1][s] : *(const bf16x8*)(kbase + (size_t)(16 * tj + r) * 512 + 32 * s + 8 * q); ckk = MFMA16(ak[s], bk, ckk); cqk = MFMA16(aq[s], bk, cqk); }
.LBB0_275:
	s_or_b64 exec, exec, vcc
	s_waitcnt lgkmcnt(1)
	v_mul_f32_e32 v65, v70, v65
	v_mul_f32_e32 v65, v65, v76
	v_cndmask_b32_e64 v70, 0, v65, s[50:51]
	s_waitcnt lgkmcnt(0)
	v_mul_f32_e32 v65, v71, v66
	v_mul_f32_e32 v65, v65, v64
	v_mul_f32_e32 v64, v67, v64
	s_mov_b32 s14, 0x8000
	v_cndmask_b32_e64 v64, v64, 0, s[52:53]
	v_add_co_u32_e32 v78, vcc, s14, v126
	v_cvt_pk_bf16_f32 v64, v64, v64
	global_store_short v215, v64, s[26:27]
	s_nop 0
	v_addc_co_u32_e32 v79, vcc, 0, v127, vcc
	s_mov_b64 s[100:101], 0x4000
	v_lshl_add_u64 v[250:251], v[78:79], 0, s[100:101]
	v_cndmask_b32_e64 v71, 0, v65, s[56:57]
	global_load_dwordx4 v[64:67], v[78:79], off
	v_mul_f32_e32 v69, v69, v75
	v_mul_f32_e32 v69, v69, v77
	global_load_dwordx4 v[74:77], v[78:79], off offset:64
	global_load_dwordx4 v[234:237], v[78:79], off offset:128
	global_load_dwordx4 v[238:241], v[78:79], off offset:192
	global_load_dwordx4 v[242:245], v[250:251], off
	global_load_dwordx4 v[246:249], v[250:251], off offset:64
	v_mul_f32_e32 v68, v68, v73
	v_readlane_b32 s40, v252, 27
	v_mul_f32_e32 v68, v68, v80
	v_readlane_b32 s41, v252, 28
	v_cndmask_b32_e64 v69, v69, 0, s[36:37]
	s_nop 0
	v_cndmask_b32_e64 v68, 0, v68, s[40:41]
	ds_write_b128 v216, v[68:71] offset:1024
	s_waitcnt vmcnt(5)
	v_mfma_f32_16x16x32_bf16 v[68:71], v[56:59], v[64:67], 0
	v_mfma_f32_16x16x32_bf16 v[64:67], v[60:63], v[64:67], 0
	s_waitcnt vmcnt(4)
	v_mfma_f32_16x16x32_bf16 v[68:71], v[48:51], v[74:77], v[68:71]
	v_mfma_f32_16x16x32_bf16 v[64:67], v[52:55], v[74:77], v[64:67]
	s_waitcnt vmcnt(3)
	v_mfma_f32_16x16x32_bf16 v[68:71], v[40:43], v[234:237], v[68:71]
	v_mfma_f32_16x16x32_bf16 v[64:67], v[44:47], v[234:237], v[64:67]
	s_waitcnt vmcnt(2)
	v_mfma_f32_16x16x32_bf16 v[68:71], v[32:35], v[238:241], v[68:71]
	v_mfma_f32_16x16x32_bf16 v[64:67], v[36:39], v[238:241], v[64:67]
	global_load_dwordx4 v[234:237], v[250:251], off offset:128
	global_load_dwordx4 v[238:241], v[250:251], off offset:192
	ds_read_b32 v74, v137 offset:128
	ds_read_b32 v73, v138 offset:256
	s_and_saveexec_b64 vcc, s[60:61]
	s_cbranch_execz .LBB0_277
	ds_read_b32 v72, v138
	s_waitcnt lgkmcnt(0)
	v_sub_f32_e32 v72, v72, v74
	v_mul_f32_e32 v72, 0x3fb8aa3b, v72
	v_exp_f32_e32 v72, v72

; #define MFMA16(a, b, c) __builtin_amdgcn_mfma_f32_16x16x32_bf16((a), (b), (c), 0, 0, 0)
; __device__ __forceinline__ void phase_prep(const Args& a, PG8_LAS unsigned char* lds) {
;     ...
; #pragma unroll
;             for (int tj = 0; tj < 4; ++tj) {
;                 f32x4 ckk = {0.f, 0.f, 0.f, 0.f}, cqk = {0.f, 0.f, 0.f, 0.f};
; #pragma unroll
;                 for (int s = 0; s < 4; ++s) { const bf16x8 bk = (tj < 2) ? bkf[tj & 1][s] : *(const bf16x8*)(kbase + (size_t)(16 * tj + r) * 512 + 32 * s + 8 * q); ckk = MFMA16(ak[s], bk, ckk); cqk = MFMA16(aq[s], bk, cqk); }
.LBB0_283:
	s_or_b64 exec, exec, vcc
	s_waitcnt lgkmcnt(3)
	v_mul_f32_e32 v68, v68, v73
	s_waitcnt lgkmcnt(2)
	v_mul_f32_e32 v69, v69, v75
	s_waitcnt lgkmcnt(1)
	v_mul_f32_e32 v70, v70, v78
	s_waitcnt lgkmcnt(0)
	v_mul_f32_e32 v66, v71, v66
	v_mul_f32_e32 v68, v68, v72
	v_mul_f32_e32 v69, v69, v77
	v_mul_f32_e32 v70, v70, v76
	v_mul_f32_e32 v66, v66, v65
	v_mul_f32_e32 v65, v67, v65
	v_cndmask_b32_e64 v68, 0, v68, s[64:65]
	v_cndmask_b32_e64 v69, v69, 0, s[58:59]
	v_cndmask_b32_e64 v70, 0, v70, s[42:43]
	v_cndmask_b32_e64 v71, 0, v66, s[80:81]
	v_cndmask_b32_e64 v65, v65, 0, s[76:77]
	v_cvt_pk_bf16_f32 v65, v65, v65
	ds_write_b128 v221, v[68:71] offset:1024
	v_add_co_u32_e32 v70, vcc, s35, v126
	global_store_short v220, v65, s[26:27]
	s_nop 0
	v_addc_co_u32_e32 v71, vcc, 0, v127, vcc
	s_waitcnt vmcnt(4)
	v_mfma_f32_16x16x32_bf16 v[56:59], v[56:59], v[242:245], 0
	v_mfma_f32_16x16x32_bf16 v[60:63], v[60:63], v[242:245], 0
	v_mfma_f32_16x16x32_bf16 v[48:51], v[48:51], v[246:249], v[56:59]
	s_nop 3
	v_mfma_f32_16x16x32_bf16 v[52:55], v[52:55], v[246:249], v[60:63]
	v_mfma_f32_16x16x32_bf16 v[40:43], v[40:43], v[234:237], v[48:51]
	s_nop 2
	v_mfma_f32_16x16x32_bf16 v[44:47], v[44:47], v[234:237], v[52:55]
	v_mfma_f32_16x16x32_bf16 v[40:43], v[32:35], v[238:241], v[40:43]
	v_mfma_f32_16x16x32_bf16 v[32:35], v[36:39], v[238:241], v[44:47]
	ds_read_b32 v37, v137 offset:192
	ds_read_b32 v36, v138 offset:256
	s_and_saveexec_b64 vcc, s[84:85]
	s_cbranch_execz .LBB0_285
	ds_read_b32 v38, v138
	s_waitcnt lgkmcnt(0)
	v_sub_f32_e32 v38, v38, v37
	v_mul_f32_e32 v38, 0x3fb8aa3b, v38
	v_exp_f32_e32 v64, v38

	.amdhsa_kernel _Z4mega4Args
		.amdhsa_group_segment_fixed_size 0
		.amdhsa_private_segment_fixed_size 0
		.amdhsa_kernarg_size 416
		.amdhsa_user_sgpr_count 2
		.amdhsa_user_sgpr_dispatch_ptr 0
		.amdhsa_user_sgpr_queue_ptr 0
		.amdhsa_user_sgpr_kernarg_segment_ptr 1
		.amdhsa_user_sgpr_dispatch_id 0
		.amdhsa_user_sgpr_kernarg_preload_length 0
		.amdhsa_user_sgpr_kernarg_preload_offset 0
		.amdhsa_user_sgpr_private_segment_size 0
		.amdhsa_uses_dynamic_stack 0
		.amdhsa_enable_private_segment 0
		.amdhsa_system_sgpr_workgroup_id_x 1
		.amdhsa_system_sgpr_workgroup_id_y 0
		.amdhsa_system_sgpr_workgroup_id_z 0
		.amdhsa_system_sgpr_workgroup_info 0
		.amdhsa_system_vgpr_workitem_id 2
		.amdhsa_next_free_vgpr 254
		.amdhsa_next_free_sgpr 102
		.amdhsa_accum_offset 256
		.amdhsa_reserve_vcc 1
		.amdhsa_float_round_mode_32 0
		.amdhsa_float_round_mode_16_64 0
		.amdhsa_float_denorm_mode_32 3
		.amdhsa_float_denorm_mode_16_64 3
		.amdhsa_dx10_clamp 1
		.amdhsa_ieee_mode 1
		.amdhsa_fp16_overflow 0
		.amdhsa_tg_split 0
		.amdhsa_exception_fp_ieee_invalid_op 0
		.amdhsa_exception_fp_denorm_src 0
		.amdhsa_exception_fp_ieee_div_zero 0
		.amdhsa_exception_fp_ieee_overflow 0
		.amdhsa_exception_fp_ieee_underflow 0
		.amdhsa_exception_fp_ieee_inexact 0
		.amdhsa_exception_int_div_zero 0
	.end_amdhsa_kernel

; __global__ void __launch_bounds__(NT) mega(Args a) {
;     extern __shared__ __attribute__((aligned(16))) unsigned char lds_raw[];
amdhsa.kernels:
  - .agpr_count:     0
    .args:
      - .offset:         0
        .size:           160
        .value_kind:     by_value
      - .offset:         160
        .size:           4
        .value_kind:     hidden_block_count_x
      - .offset:         164
        .size:           4
        .value_kind:     hidden_block_count_y
      - .offset:         168
        .size:           4
        .value_kind:     hidden_block_count_z
      - .offset:         172
        .size:           2
        .value_kind:     hidden_group_size_x
      - .offset:         174
        .size:           2
        .value_kind:     hidden_group_size_y
      - .offset:         176
        .size:           2
        .value_kind:     hidden_group_size_z
      - .offset:         178
        .size:           2
        .value_kind:     hidden_remainder_x
      - .offset:         180
        .size:           2
        .value_kind:     hidden_remainder_y
      - .offset:         182
        .size:           2
        .value_kind:     hidden_remainder_z
      - .offset:         200
        .size:           8
        .value_kind:     hidden_global_offset_x
      - .offset:         208
        .size:           8
        .value_kind:     hidden_global_offset_y
      - .offset:         216
        .size:           8
        .value_kind:     hidden_global_offset_z
      - .offset:         224
        .size:           2
        .value_kind:     hidden_grid_dims
      - .offset:         248
        .size:           8
        .value_kind:     hidden_multigrid_sync_arg
      - .offset:         280
        .size:           4
        .value_kind:     hidden_dynamic_lds_size
    .group_segment_fixed_size: 0
    .kernarg_segment_align: 8
    .kernarg_segment_size: 416
    .language:       OpenCL C
    .language_version:
      - 2
      - 0
    .max_flat_workgroup_size: 512
    .name:           _Z4mega4Args
    .private_segment_fixed_size: 0
    .sgpr_count:     108
    .sgpr_spill_count: 98
    .symbol:         _Z4mega4Args.kd
    .uniform_work_group_size: 1
    .uses_dynamic_stack: false
    .vgpr_count:     254
    .vgpr_spill_count: 0
    .wavefront_size: 64
